# hgrn pass1: per-element exec-mask diamonds of the decay factor replaced by one v_cndmask-selected expression (same bits, 4 VALU per element)
# baseline (speedup 1.0000x reference)
.LBB0_388:
	s_or_b64 exec, exec, s[0:1]
	v_cndmask_b32_e32 v33, 0, v34, vcc
	v_cndmask_b32_e64 v34, 0, v35, s[38:39]
	v_add_f32_e32 v33, v33, v34
	v_cndmask_b32_e64 v32, 0, v32, s[40:41]
	v_add_f32_e32 v100, v33, v32
	v_add_f32_e32 v33, v130, v100
	v_sub_f32_e32 v34, v95, v39
	v_mul_f32_e32 v34, 0x3fb8aa3b, v34
	v_exp_f32_e32 v98, v34
	v_cndmask_b32_e64 v244, v39, v95, s[38:39]
	v_cndmask_b32_e64 v245, v98, 1.0, s[38:39]
	v_sub_f32_e32 v32, v244, v33
	v_mul_f32_e32 v32, 0x3fb8aa3b, v32
	v_exp_f32_e32 v32, v32
	s_nop 0
	v_mul_f32_e32 v32, v245, v32
	v_add_f32_e32 v34, v129, v100
	v_sub_f32_e32 v33, v244, v34
	v_mul_f32_e32 v33, 0x3fb8aa3b, v33
	v_exp_f32_e32 v33, v33
	s_nop 0
	v_mul_f32_e32 v33, v245, v33
	v_mul_f32_e32 v34, 0x3fb8aa3b, v128
	v_mul_f32_e32 v35, 0x3fb8aa3b, v127
	v_exp_f32_e32 v34, v34
	v_exp_f32_e32 v35, v35
	v_sub_f32_e32 v34, 1.0, v34
	v_sub_f32_e32 v35, 1.0, v35
	v_mul_f32_e32 v32, v35, v32
	v_mul_f32_e32 v33, v34, v33
	v_add_f32_e32 v34, v126, v100
	v_cvt_pk_bf16_f32 v32, v32, v33
	v_sub_f32_e32 v33, v244, v34
	v_mul_f32_e32 v33, 0x3fb8aa3b, v33
	v_exp_f32_e32 v33, v33
	s_nop 0
	v_mul_f32_e32 v33, v245, v33
	v_add_f32_e32 v35, v125, v100
	v_sub_f32_e32 v34, v244, v35
	v_mul_f32_e32 v34, 0x3fb8aa3b, v34
	v_exp_f32_e32 v34, v34
	s_nop 0
	v_mul_f32_e32 v34, v245, v34
	v_mul_f32_e32 v35, 0x3fb8aa3b, v124
	v_mul_f32_e32 v36, 0x3fb8aa3b, v123
	v_exp_f32_e32 v35, v35
	v_exp_f32_e32 v36, v36
	v_sub_f32_e32 v35, 1.0, v35
	v_sub_f32_e32 v36, 1.0, v36
	v_mul_f32_e32 v33, v36, v33
	v_mul_f32_e32 v34, v35, v34
	v_add_f32_e32 v35, v122, v100
	v_cvt_pk_bf16_f32 v33, v33, v34
	v_sub_f32_e32 v34, v244, v35
	v_mul_f32_e32 v34, 0x3fb8aa3b, v34
	v_exp_f32_e32 v34, v34
	s_nop 0
	v_mul_f32_e32 v34, v245, v34
	v_add_f32_e32 v36, v121, v100
	v_sub_f32_e32 v35, v244, v36
	v_mul_f32_e32 v35, 0x3fb8aa3b, v35
	v_exp_f32_e32 v35, v35
	s_nop 0
	v_mul_f32_e32 v35, v245, v35
	v_mul_f32_e32 v36, 0x3fb8aa3b, v120
	v_mul_f32_e32 v37, 0x3fb8aa3b, v119
	v_exp_f32_e32 v36, v36
	v_exp_f32_e32 v37, v37
	v_sub_f32_e32 v36, 1.0, v36
	v_sub_f32_e32 v37, 1.0, v37
	v_mul_f32_e32 v34, v37, v34
	v_mul_f32_e32 v35, v36, v35
	v_add_f32_e32 v36, v118, v100
	v_cvt_pk_bf16_f32 v34, v34, v35
	v_sub_f32_e32 v35, v244, v36
	v_mul_f32_e32 v35, 0x3fb8aa3b, v35
	v_exp_f32_e32 v35, v35
	s_nop 0
	v_mul_f32_e32 v35, v245, v35
	v_add_f32_e32 v37, v117, v100
	v_sub_f32_e32 v36, v244, v37
	v_mul_f32_e32 v36, 0x3fb8aa3b, v36
	v_exp_f32_e32 v36, v36
	s_nop 0
	v_mul_f32_e32 v36, v245, v36
	v_mul_f32_e32 v37, 0x3fb8aa3b, v116
	v_mul_f32_e32 v38, 0x3fb8aa3b, v115
	v_exp_f32_e32 v37, v37
	v_exp_f32_e32 v38, v38
	v_sub_f32_e32 v37, 1.0, v37
	v_sub_f32_e32 v38, 1.0, v38
	v_mul_f32_e32 v35, v38, v35
	v_mul_f32_e32 v36, v37, v36
	v_add_f32_e32 v37, v114, v100
	v_cvt_pk_bf16_f32 v35, v35, v36
	v_sub_f32_e32 v36, v244, v37
	v_mul_f32_e32 v36, 0x3fb8aa3b, v36
	v_exp_f32_e32 v36, v36
	s_nop 0
	v_mul_f32_e32 v36, v245, v36
	v_add_f32_e32 v38, v113, v100
	v_sub_f32_e32 v37, v244, v38
	v_mul_f32_e32 v37, 0x3fb8aa3b, v37
	v_exp_f32_e32 v37, v37
	s_nop 0
	v_mul_f32_e32 v37, v245, v37
	v_mul_f32_e32 v38, 0x3fb8aa3b, v112
	v_mul_f32_e32 v105, 0x3fb8aa3b, v111
	v_exp_f32_e32 v38, v38
	v_exp_f32_e32 v105, v105
	v_sub_f32_e32 v38, 1.0, v38
	v_sub_f32_e32 v105, 1.0, v105
	v_mul_f32_e32 v36, v105, v36
	v_mul_f32_e32 v37, v38, v37
	v_add_f32_e32 v38, v100, v110
	v_cvt_pk_bf16_f32 v36, v36, v37
	v_sub_f32_e32 v37, v244, v38
	v_mul_f32_e32 v37, 0x3fb8aa3b, v37
	v_exp_f32_e32 v37, v37
	s_nop 0
	v_mul_f32_e32 v37, v245, v37
	v_add_f32_e32 v105, v100, v109
	v_sub_f32_e32 v38, v244, v105
	v_mul_f32_e32 v38, 0x3fb8aa3b, v38
	v_exp_f32_e32 v38, v38
	s_nop 0
	v_mul_f32_e32 v38, v245, v38
	v_mul_f32_e32 v104, 0x3fb8aa3b, v104
	v_mul_f32_e32 v103, 0x3fb8aa3b, v103
	v_exp_f32_e32 v104, v104
	v_exp_f32_e32 v103, v103
	v_add_f32_e32 v102, v100, v102
	v_sub_f32_e32 v104, 1.0, v104
	v_sub_f32_e32 v103, 1.0, v103
	v_mul_f32_e32 v37, v103, v37
	v_mul_f32_e32 v38, v104, v38
	v_cvt_pk_bf16_f32 v37, v37, v38
	v_sub_f32_e32 v38, v244, v102
	v_mul_f32_e32 v38, 0x3fb8aa3b, v38
	v_exp_f32_e32 v38, v38
	s_nop 0
	v_mul_f32_e32 v38, v245, v38
	v_add_f32_e32 v102, v100, v101
	v_sub_f32_e32 v101, v244, v102
	v_mul_f32_e32 v101, 0x3fb8aa3b, v101
	v_exp_f32_e32 v101, v101
	s_nop 0
	v_mul_f32_e32 v101, v245, v101
	v_mul_f32_e32 v99, 0x3fb8aa3b, v99
	v_mul_f32_e32 v97, 0x3fb8aa3b, v97
	v_exp_f32_e32 v99, v99
	v_exp_f32_e32 v97, v97
	v_sub_f32_e32 v99, 1.0, v99
	v_sub_f32_e32 v97, 1.0, v97
	v_mul_f32_e32 v38, v97, v38
	v_mul_f32_e32 v97, v99, v101
	v_cvt_pk_bf16_f32 v38, v38, v97
	v_add_f32_e32 v97, v100, v96
	v_sub_f32_e32 v96, v244, v97
	v_mul_f32_e32 v96, 0x3fb8aa3b, v96
	v_exp_f32_e32 v96, v96
	s_nop 0
	v_mul_f32_e32 v96, v245, v96
	v_add_f32_e32 v97, v100, v94
	s_and_saveexec_b64 s[0:1], s[38:39]
	s_xor_b64 s[0:1], exec, s[0:1]
	v_sub_f32_e32 v39, v95, v97
	v_mul_f32_e32 v39, 0x3fb8aa3b, v39
	v_exp_f32_e32 v94, v39
	s_andn2_saveexec_b64 s[0:1], s[0:1]
	s_cbranch_execz .LBB0_385
	v_sub_f32_e32 v39, v39, v97
	v_mul_f32_e32 v39, 0x3fb8aa3b, v39
	v_exp_f32_e32 v39, v39
	s_nop 0
	v_mul_f32_e32 v94, v98, v39
	s_branch .LBB0_385
